# K rms-norm precomputed once per K tile in the mixer-prep phase, attention stages K by plain copy
# baseline (speedup 1.0000x reference)
; #define LAS __attribute__((address_space(3)))
; __device__ __forceinline__ unsigned pk2(float lo, float hi) { f32x2_t v = {lo, hi}; bf16x2_t b = __builtin_convertvector(v, bf16x2_t); return __builtin_bit_cast(unsigned, b); }
; __device__ __forceinline__ void unpack8(u32x4v w, float* f) { f[0] = bflo(w.x); f[1] = bfhi(w.x); f[2] = bflo(w.y); f[3] = bfhi(w.y); f[4] = bflo(w.z); f[5] = bfhi(w.z); f[6] = bflo(w.w); f[7] = bfhi(w.w); }
; #define ATT_FETCH(KT) do { _Pragma("unroll") for (int hh = 0; hh < 2; ++hh) { const bf16* krow = P + (seq0 + 128 * (KT) + 64 * hh + skey) * PW; \
;         gk0[hh] = *(const u32x4v*)(krow + KC + part * 16); gk1[hh] = *(const u32x4v*)(krow + KC + part * 16 + 8); \
;         gv0[hh] = *(const u32x4v*)(krow + VC + part * 16); gv1[hh] = *(const u32x4v*)(krow + VC + part * 16 + 8); } } while (0)
; __device__ __forceinline__ void attn_unit(const Args& c, int l, int b, int h, int qb, float lam, float lam_init, LAS unsigned char* lds) {
;     ...
;         for (int hh = 0; hh < 2; ++hh) {
;             const int kr = skey + 64 * hh;
;             float f[16]; unpack8(gk0[hh], f); unpack8(gk1[hh], f + 8);
;             float kw[16];
; #pragma unroll
;             for (int e4 = 0; e4 < 4; ++e4) { const f32x4 t4 = ((const f32x4*)kwp)[e4]; kw[4 * e4] = t4.x; kw[4 * e4 + 1] = t4.y; kw[4 * e4 + 2] = t4.z; kw[4 * e4 + 3] = t4.w; }
;             float ss = 0.f;
; #pragma unroll
;             for (int e = 0; e < 16; ++e) ss += f[e] * f[e];
;             ss += __shfl_xor(ss, 1); ss += __shfl_xor(ss, 2);
;             const float sc = rsqrtf(ss * (1.f / 64.f) + 1e-6f);
;             u32x4v o;
;             o.x = pk2(f[0] * sc * kw[0], f[1] * sc * kw[1]); o.y = pk2(f[2] * sc * kw[2], f[3] * sc * kw[3]); o.z = pk2(f[4] * sc * kw[4], f[5] * sc * kw[5]); o.w = pk2(f[6] * sc * kw[6], f[7] * sc * kw[7]);
;             *(LAS u32x4v*)(Kt + kr * 136 + part * 16) = o;
;             o.x = pk2(f[8] * sc * kw[8], f[9] * sc * kw[9]); o.y = pk2(f[10] * sc * kw[10], f[11] * sc * kw[11]); o.z = pk2(f[12] * sc * kw[12], f[13] * sc * kw[13]); o.w = pk2(f[14] * sc * kw[14], f[15] * sc * kw[15]);
;             *(LAS u32x4v*)(Kt + kr * 136 + part * 16 + 8) = o;
;             *(LAS u32x4v*)(Vs + kr * 136 + part * 16) = gv0[hh]; *(LAS u32x4v*)(Vs + kr * 136 + part * 16 + 8) = gv1[hh];
;         }
;         if (kt + 1 < NT) ATT_FETCH(kt + 1);
.LBB0_245:
	s_waitcnt lgkmcnt(0)
	s_barrier
	s_waitcnt vmcnt(0)
	ds_write_b128 v211, v[66:69]
	ds_write_b128 v211, v[70:73] offset:16
	ds_write_b128 v211, v[90:93] offset:17408
	ds_write_b128 v211, v[94:97] offset:17424
	ds_write_b128 v211, v[78:81] offset:34816
	ds_write_b128 v211, v[82:85] offset:34832
	ds_write_b128 v211, v[98:101] offset:52224
	ds_write_b128 v211, v[102:105] offset:52240
	s_cmp_ge_u32 s35, s22
	s_cbranch_scc1 .LBB0_247
	s_add_i32 s8, s18, s5
	s_add_i32 s14, s8, 0x80
	v_lshl_add_u64 v[66:67], s[14:15], 0, v[186:187]
	s_add_i32 s14, s8, 0xc0
	v_mov_b64_e32 v[90:91], s[2:3]
	v_lshl_add_u64 v[92:93], s[14:15], 0, v[186:187]
	v_mad_u64_u32 v[78:79], s[6:7], v66, s27, v[90:91]
	v_mad_u64_u32 v[98:99], s[6:7], v92, s27, v[90:91]
	v_mad_i32_i24 v79, v67, s27, v79
	s_mov_b32 s21, s15
	s_mov_b32 s29, s15
	v_mad_i32_i24 v99, v93, s27, v99
	v_lshl_add_u64 v[66:67], v[78:79], 0, s[20:21]
	v_lshl_add_u64 v[78:79], v[78:79], 0, s[28:29]
	v_lshl_add_u64 v[90:91], v[98:99], 0, s[20:21]
	v_lshl_add_u64 v[98:99], v[98:99], 0, s[28:29]
	v_lshl_add_u64 v[70:71], v[66:67], 0, v[0:1]
	v_lshl_add_u64 v[82:83], v[78:79], 0, v[0:1]
	v_lshl_add_u64 v[94:95], v[90:91], 0, v[0:1]
	v_lshl_add_u64 v[102:103], v[98:99], 0, v[0:1]
	global_load_dwordx4 v[66:69], v[70:71], off
	s_nop 0
	global_load_dwordx4 v[70:73], v[70:71], off offset:16
	s_nop 0
	global_load_dwordx4 v[78:81], v[82:83], off
	s_nop 0
	global_load_dwordx4 v[82:85], v[82:83], off offset:16
	s_nop 0
	global_load_dwordx4 v[90:93], v[94:95], off
	s_nop 0
	global_load_dwordx4 v[94:97], v[94:95], off offset:16
	s_nop 0
	global_load_dwordx4 v[98:101], v[102:103], off
	s_nop 0
	global_load_dwordx4 v[102:105], v[102:103], off offset:16

; __device__ __forceinline__ void unpack8(u32x4v w, float* f) { f[0] = bflo(w.x); f[1] = bfhi(w.x); f[2] = bflo(w.y); f[3] = bfhi(w.y); f[4] = bflo(w.z); f[5] = bfhi(w.z); f[6] = bflo(w.w); f[7] = bfhi(w.w); }
; __device__ __forceinline__ void attn_unit(const Args& c, int l, int b, int h, int qb, float lam, float lam_init, LAS unsigned char* lds) {
;     ...
;             float f[16]; unpack8(gk0[hh], f); unpack8(gk1[hh], f + 8);
;             float kw[16];
; #pragma unroll
;             for (int e4 = 0; e4 < 4; ++e4) { const f32x4 t4 = ((const f32x4*)kwp)[e4]; kw[4 * e4] = t4.x; kw[4 * e4 + 1] = t4.y; kw[4 * e4 + 2] = t4.z; kw[4 * e4 + 3] = t4.w; }
.LBB0_622:
	v_readlane_b32 s2, v252, 59
	v_readlane_b32 s3, v252, 60
	v_readlane_b32 s4, v251, 0
	v_readlane_b32 s5, v251, 1
	v_readlane_b32 s20, v253, 19
	v_readlane_b32 s21, v250, 50
	s_nop 3
	s_add_u32 s24, s2, 0xa800000
	s_addc_u32 s25, s3, 0
	s_load_dwordx2 s[16:17], s[4:5], 0xb8
	s_lshr_b32 s21, s21, 1
	v_and_b32_e32 v4, 3, v179
	v_lshlrev_b32_e32 v4, 6, v4
	v_lshrrev_b32_e32 v6, 3, v179
	v_and_b32_e32 v5, 7, v179
	s_waitcnt lgkmcnt(0)
	s_add_u32 s16, s16, s21
	s_addc_u32 s17, s17, 0
	global_load_dwordx4 v[24:27], v4, s[16:17]
	global_load_dwordx4 v[28:31], v4, s[16:17] offset:16
	global_load_dwordx4 v[32:35], v4, s[16:17] offset:32
	global_load_dwordx4 v[36:39], v4, s[16:17] offset:48
; #define LAS __attribute__((address_space(3)))
; __device__ __forceinline__ unsigned pk2(float lo, float hi) { f32x2_t v = {lo, hi}; bf16x2_t b = __builtin_convertvector(v, bf16x2_t); return __builtin_bit_cast(unsigned, b); }
; __device__ __forceinline__ void unpack8(u32x4v w, float* f) { f[0] = bflo(w.x); f[1] = bfhi(w.x); f[2] = bflo(w.y); f[3] = bfhi(w.y); f[4] = bflo(w.z); f[5] = bfhi(w.z); f[6] = bflo(w.w); f[7] = bfhi(w.w); }
; __device__ __forceinline__ void attn_unit(const Args& c, int l, int b, int h, int qb, float lam, float lam_init, LAS unsigned char* lds) {
;     ...
;         for (int hh = 0; hh < 2; ++hh) {
;             const int kr = skey + 64 * hh;
;             float f[16]; unpack8(gk0[hh], f); unpack8(gk1[hh], f + 8);
;             float kw[16];
; #pragma unroll
;             for (int e4 = 0; e4 < 4; ++e4) { const f32x4 t4 = ((const f32x4*)kwp)[e4]; kw[4 * e4] = t4.x; kw[4 * e4 + 1] = t4.y; kw[4 * e4 + 2] = t4.z; kw[4 * e4 + 3] = t4.w; }
;             float ss = 0.f;
; #pragma unroll
;             for (int e = 0; e < 16; ++e) ss += f[e] * f[e];
;             ss += __shfl_xor(ss, 1); ss += __shfl_xor(ss, 2);
;             const float sc = rsqrtf(ss * (1.f / 64.f) + 1e-6f);
;             u32x4v o;
;             o.x = pk2(f[0] * sc * kw[0], f[1] * sc * kw[1]); o.y = pk2(f[2] * sc * kw[2], f[3] * sc * kw[3]); o.z = pk2(f[4] * sc * kw[4], f[5] * sc * kw[5]); o.w = pk2(f[6] * sc * kw[6], f[7] * sc * kw[7]);
;             *(LAS u32x4v*)(Kt + kr * 136 + part * 16) = o;
;             o.x = pk2(f[8] * sc * kw[8], f[9] * sc * kw[9]); o.y = pk2(f[10] * sc * kw[10], f[11] * sc * kw[11]); o.z = pk2(f[12] * sc * kw[12], f[13] * sc * kw[13]); o.w = pk2(f[14] * sc * kw[14], f[15] * sc * kw[15]);
;             *(LAS u32x4v*)(Kt + kr * 136 + part * 16 + 8) = o;
.Lkn_loop:
	s_and_b32 s0, s20, 15
	s_lshr_b32 s1, s20, 4
	s_and_b32 s1, s1, 7
	s_lshr_b32 s2, s20, 7
	s_lshl_b32 s2, s2, 11
	s_lshl_b32 s0, s0, 7
	s_or_b32 s0, s0, s2
	s_lshl_b32 s1, s1, 8
	s_addk_i32 s1, 0x2700
	v_add_u32_e32 v2, s0, v6
	v_mul_u32_u24_e32 v2, 0x3800, v2
	v_lshl_add_u32 v2, v5, 5, v2
	v_add_u32_e32 v2, s1, v2
	v_add_u32_e32 v3, 0xe0000, v2
	global_load_dwordx4 v[8:11], v2, s[24:25]
	global_load_dwordx4 v[12:15], v2, s[24:25] offset:16
	global_load_dwordx4 v[16:19], v3, s[24:25]
	global_load_dwordx4 v[20:23], v3, s[24:25] offset:16
	s_waitcnt vmcnt(0)
	v_lshlrev_b32_e32 v56, 16, v8
	v_and_b32_e32 v57, 0xffff0000, v8
	v_lshlrev_b32_e32 v58, 16, v9
	v_and_b32_e32 v59, 0xffff0000, v9
	v_lshlrev_b32_e32 v60, 16, v10
	v_and_b32_e32 v61, 0xffff0000, v10
	v_lshlrev_b32_e32 v62, 16, v11
	v_and_b32_e32 v63, 0xffff0000, v11
	v_lshlrev_b32_e32 v64, 16, v12
	v_and_b32_e32 v65, 0xffff0000, v12
	v_lshlrev_b32_e32 v66, 16, v13
	v_and_b32_e32 v67, 0xffff0000, v13
	v_lshlrev_b32_e32 v68, 16, v14
	v_and_b32_e32 v69, 0xffff0000, v14
	v_lshlrev_b32_e32 v70, 16, v15
	v_and_b32_e32 v71, 0xffff0000, v15
	v_mul_f32_e32 v72, v56, v56
	v_fmac_f32_e32 v72, v57, v57
	v_fmac_f32_e32 v72, v58, v58
	v_fmac_f32_e32 v72, v59, v59
	v_fmac_f32_e32 v72, v60, v60
	v_fmac_f32_e32 v72, v61, v61
	v_fmac_f32_e32 v72, v62, v62
	v_fmac_f32_e32 v72, v63, v63
	v_fmac_f32_e32 v72, v64, v64
	v_fmac_f32_e32 v72, v65, v65
	v_fmac_f32_e32 v72, v66, v66
	v_fmac_f32_e32 v72, v67, v67
	v_fmac_f32_e32 v72, v68, v68
	v_fmac_f32_e32 v72, v69, v69
	v_fmac_f32_e32 v72, v70, v70
	v_fmac_f32_e32 v72, v71, v71
	s_nop 1
	v_add_f32_dpp v72, v72, v72 quad_perm:[1,0,3,2] row_mask:0xf bank_mask:0xf bound_ctrl:1
	s_nop 1
	v_add_f32_dpp v72, v72, v72 quad_perm:[2,3,0,1] row_mask:0xf bank_mask:0xf bound_ctrl:1
	v_fmamk_f32 v73, v72, 0x3c800000, v178
	v_rsq_f32_e32 v74, v73
	s_nop 0
	v_mul_f32_e32 v56, v74, v56
	v_mul_f32_e32 v56, v24, v56
	v_mul_f32_e32 v57, v74, v57
	v_mul_f32_e32 v57, v25, v57
	v_cvt_pk_bf16_f32 v8, v56, v57
	v_mul_f32_e32 v58, v74, v58
	v_mul_f32_e32 v58, v26, v58
	v_mul_f32_e32 v59, v74, v59
	v_mul_f32_e32 v59, v27, v59
	v_cvt_pk_bf16_f32 v9, v58, v59
	v_mul_f32_e32 v60, v74, v60
	v_mul_f32_e32 v60, v28, v60
	v_mul_f32_e32 v61, v74, v61
	v_mul_f32_e32 v61, v29, v61
	v_cvt_pk_bf16_f32 v10, v60, v61
	v_mul_f32_e32 v62, v74, v62
	v_mul_f32_e32 v62, v30, v62
	v_mul_f32_e32 v63, v74, v63
	v_mul_f32_e32 v63, v31, v63
	v_cvt_pk_bf16_f32 v11, v62, v63
	v_mul_f32_e32 v64, v74, v64
	v_mul_f32_e32 v64, v32, v64
	v_mul_f32_e32 v65, v74, v65
	v_mul_f32_e32 v65, v33, v65
	v_cvt_pk_bf16_f32 v12, v64, v65
	v_mul_f32_e32 v66, v74, v66
	v_mul_f32_e32 v66, v34, v66
	v_mul_f32_e32 v67, v74, v67
	v_mul_f32_e32 v67, v35, v67
	v_cvt_pk_bf16_f32 v13, v66, v67
	v_mul_f32_e32 v68, v74, v68
	v_mul_f32_e32 v68, v36, v68
	v_mul_f32_e32 v69, v74, v69
	v_mul_f32_e32 v69, v37, v69
	v_cvt_pk_bf16_f32 v14, v68, v69
	v_mul_f32_e32 v70, v74, v70
	v_mul_f32_e32 v70, v38, v70
	v_mul_f32_e32 v71, v74, v71
	v_mul_f32_e32 v71, v39, v71
	v_cvt_pk_bf16_f32 v15, v70, v71
	v_lshlrev_b32_e32 v56, 16, v16
	v_and_b32_e32 v57, 0xffff0000, v16
	v_lshlrev_b32_e32 v58, 16, v17
	v_and_b32_e32 v59, 0xffff0000, v17
	v_lshlrev_b32_e32 v60, 16, v18
	v_and_b32_e32 v61, 0xffff0000, v18
	v_lshlrev_b32_e32 v62, 16, v19
	v_and_b32_e32 v63, 0xffff0000, v19
	v_lshlrev_b32_e32 v64, 16, v20
	v_and_b32_e32 v65, 0xffff0000, v20
	v_lshlrev_b32_e32 v66, 16, v21
	v_and_b32_e32 v67, 0xffff0000, v21
	v_lshlrev_b32_e32 v68, 16, v22
	v_and_b32_e32 v69, 0xffff0000, v22
	v_lshlrev_b32_e32 v70, 16, v23
	v_and_b32_e32 v71, 0xffff0000, v23
	v_mul_f32_e32 v72, v56, v56
	v_fmac_f32_e32 v72, v57, v57
	v_fmac_f32_e32 v72, v58, v58
	v_fmac_f32_e32 v72, v59, v59
	v_fmac_f32_e32 v72, v60, v60
	v_fmac_f32_e32 v72, v61, v61
	v_fmac_f32_e32 v72, v62, v62
	v_fmac_f32_e32 v72, v63, v63
	v_fmac_f32_e32 v72, v64, v64
	v_fmac_f32_e32 v72, v65, v65
	v_fmac_f32_e32 v72, v66, v66
	v_fmac_f32_e32 v72, v67, v67
	v_fmac_f32_e32 v72, v68, v68
	v_fmac_f32_e32 v72, v69, v69
	v_fmac_f32_e32 v72, v70, v70
	v_fmac_f32_e32 v72, v71, v71
	s_nop 1
	v_add_f32_dpp v72, v72, v72 quad_perm:[1,0,3,2] row_mask:0xf bank_mask:0xf bound_ctrl:1
	s_nop 1
	v_add_f32_dpp v72, v72, v72 quad_perm:[2,3,0,1] row_mask:0xf bank_mask:0xf bound_ctrl:1
	v_fmamk_f32 v73, v72, 0x3c800000, v178
	v_rsq_f32_e32 v74, v73
	s_nop 0
	v_mul_f32_e32 v56, v74, v56
	v_mul_f32_e32 v56, v24, v56
	v_mul_f32_e32 v57, v74, v57
	v_mul_f32_e32 v57, v25, v57
	v_cvt_pk_bf16_f32 v16, v56, v57
	v_mul_f32_e32 v58, v74, v58
	v_mul_f32_e32 v58, v26, v58
	v_mul_f32_e32 v59, v74, v59
	v_mul_f32_e32 v59, v27, v59
	v_cvt_pk_bf16_f32 v17, v58, v59
	v_mul_f32_e32 v60, v74, v60
	v_mul_f32_e32 v60, v28, v60
	v_mul_f32_e32 v61, v74, v61
	v_mul_f32_e32 v61, v29, v61
	v_cvt_pk_bf16_f32 v18, v60, v61
	v_mul_f32_e32 v62, v74, v62
	v_mul_f32_e32 v62, v30, v62
	v_mul_f32_e32 v63, v74, v63
	v_mul_f32_e32 v63, v31, v63
	v_cvt_pk_bf16_f32 v19, v62, v63
	v_mul_f32_e32 v64, v74, v64
	v_mul_f32_e32 v64, v32, v64
	v_mul_f32_e32 v65, v74, v65
	v_mul_f32_e32 v65, v33, v65
	v_cvt_pk_bf16_f32 v20, v64, v65
	v_mul_f32_e32 v66, v74, v66
	v_mul_f32_e32 v66, v34, v66
	v_mul_f32_e32 v67, v74, v67
	v_mul_f32_e32 v67, v35, v67
	v_cvt_pk_bf16_f32 v21, v66, v67
	v_mul_f32_e32 v68, v74, v68
	v_mul_f32_e32 v68, v36, v68
	v_mul_f32_e32 v69, v74, v69
	v_mul_f32_e32 v69, v37, v69
	v_cvt_pk_bf16_f32 v22, v68, v69
	v_mul_f32_e32 v70, v74, v70
	v_mul_f32_e32 v70, v38, v70
	v_mul_f32_e32 v71, v74, v71
	v_mul_f32_e32 v71, v39, v71
	v_cvt_pk_bf16_f32 v23, v70, v71
	global_store_dwordx4 v2, v[8:11], s[24:25]
	global_store_dwordx4 v2, v[12:15], s[24:25] offset:16
	global_store_dwordx4 v3, v[16:19], s[24:25]
	global_store_dwordx4 v3, v[20:23], s[24:25] offset:16
	s_add_i32 s20, s20, s58
	s_cmpk_lt_i32 s20, 0x400
	s_cbranch_scc1 .Lkn_loop
	v_add_u32_e32 v0, -1, v195
	v_cmp_lt_i32_e32 vcc, v0, v52
	v_readlane_b32 s8, v253, 21
	v_readlane_b32 s10, v253, 15
	v_cndmask_b32_e32 v0, v0, v195, vcc
	v_lshlrev_b32_e32 v127, 2, v0
	v_add_u32_e32 v0, -2, v195
	v_cmp_lt_i32_e32 vcc, v0, v52
	v_readlane_b32 s12, v253, 11
	v_readlane_b32 s0, v253, 19
	v_cndmask_b32_e32 v0, v0, v195, vcc
	v_lshlrev_b32_e32 v144, 2, v0
	v_add_u32_e32 v0, -4, v195
	v_cmp_lt_i32_e32 vcc, v0, v52
	v_readlane_b32 s16, v253, 9
	v_readlane_b32 s9, v253, 22
	v_cndmask_b32_e32 v0, v0, v195, vcc
	v_lshlrev_b32_e32 v145, 2, v0
	v_add_u32_e32 v0, -8, v195
	v_cmp_lt_i32_e32 vcc, v0, v52
	v_readlane_b32 s11, v253, 16
	v_readlane_b32 s13, v253, 12
	v_cndmask_b32_e32 v0, v0, v195, vcc
	v_lshlrev_b32_e32 v146, 2, v0
	v_add_u32_e32 v0, -16, v195
	v_cmp_lt_i32_e32 vcc, v0, v52
	s_mov_b32 s17, s0
	v_readlane_b32 s1, v253, 20
	v_cndmask_b32_e32 v0, v0, v195, vcc
	v_lshlrev_b32_e32 v147, 2, v0
	v_subrev_u32_e32 v0, 32, v195
	v_cmp_lt_i32_e32 vcc, v0, v52
	s_nop 1
	v_cndmask_b32_e32 v0, v0, v195, vcc
	v_lshlrev_b32_e32 v148, 2, v0
	s_branch .LBB0_624
